# stack2 + adaLN phase: next unit's c values and first 16 w_ada rows prefetched across the unit boundary (load pipeline no longer drains between a workgroup's units)
# baseline (speedup 1.0000x reference)
.LBB8_8:
	s_or_b64 exec, exec, s[0:1]
	v_readlane_b32 s0, v254, 2
	v_readlane_b32 s1, v254, 3
	s_add_u32 s26, s0, 0x40000
	s_addc_u32 s27, s1, 0
	s_add_u32 s18, s0, 0xa0000
	s_addc_u32 s19, s1, 0
	s_add_u32 s0, s0, 0x100000
	s_addc_u32 s1, s1, 0
	s_abs_i32 s68, s3
	v_cvt_f32_u32_e32 v1, s68
	v_writelane_b32 v254, s0, 6
	v_rcp_iflag_f32_e32 v1, v1
	s_nop 0
	v_writelane_b32 v254, s1, 7
	s_sub_i32 s0, 0, s68
	v_mul_f32_e32 v1, 0x4f7ffffe, v1
	v_cvt_u32_f32_e32 v1, v1
	s_nop 0
	v_readfirstlane_b32 s35, v1
	s_mul_i32 s0, s0, s35
	s_mul_hi_u32 s0, s35, s0
	s_add_i32 s35, s35, s0
	s_mul_hi_u32 s0, s35, 0x9a0
	s_mul_i32 s0, s0, s68
	s_sub_i32 s0, 0x9a0, s0
	s_sub_i32 s1, s0, s68
	s_cmp_ge_u32 s0, s68
	s_cselect_b32 s0, s1, s0
	s_sub_i32 s1, s0, s68
	s_cmp_ge_u32 s0, s68
	s_cselect_b32 s0, s1, s0
	s_sub_i32 s69, s3, s0
	s_cmp_lt_i32 s92, 1
	s_cselect_b64 s[0:1], -1, 0
	s_cmp_gt_i32 s93, 0
	s_cselect_b64 s[4:5], -1, 0
	s_and_b64 s[6:7], s[0:1], s[4:5]
	s_and_b64 vcc, exec, s[6:7]
	s_cbranch_vccz .LBB8_33
	s_cmpk_gt_i32 s2, 0x2ff
	v_mbcnt_lo_u32_b32 v1, -1, 0
	v_mbcnt_hi_u32_b32 v1, -1, v1
	s_cbranch_scc1 .LBB8_18
	v_lshlrev_b32_e32 v2, 2, v0
	v_lshlrev_b32_e32 v3, 4, v0
	v_and_b32_e32 v67, 0xfc, v2
	s_movk_i32 s0, 0x1f00
	v_add_u32_e32 v66, 0, v3
	v_and_b32_e32 v4, 0x1c00, v3
	v_and_or_b32 v3, v3, s0, v67
	v_lshlrev_b32_e32 v5, 2, v4
	v_lshlrev_b32_e32 v6, 2, v67
	v_lshlrev_b32_e32 v3, 2, v3
	v_add3_u32 v69, 0, v5, v6
	v_or_b32_e32 v5, 0xc00, v3
	v_add_u32_e32 v70, 0, v5
	v_or_b32_e32 v5, 0xc04, v3
	v_add_u32_e32 v71, 0, v5
	v_or_b32_e32 v5, 0xc08, v3
	v_or_b32_e32 v3, 0xc0c, v3
	v_add_u32_e32 v73, 0, v3
	v_mov_b32_e32 v3, 2
	v_lshlrev_b32_sdwa v54, v3, v0 dst_sel:DWORD dst_unused:UNUSED_PAD src0_sel:DWORD src1_sel:BYTE_0
	v_mov_b32_e32 v55, 0
	v_add_u32_e32 v3, 0, v4
	v_and_b32_e32 v68, 0x1c0, v0
	v_add_u32_e32 v72, 0, v5
	v_lshl_add_u64 v[56:57], s[26:27], 0, v[54:55]
	s_mov_b32 s8, 0x8000
	v_add_u32_e32 v74, 0x8000, v3
	v_add_u32_e32 v75, 0, v2
	v_or_b32_e32 v76, 0xfffffe00, v0
	v_lshrrev_b32_e32 v77, 8, v0
	s_mov_b32 s9, 0xc000
	s_mov_b32 s10, 0x18000
	s_mov_b32 s11, 0x30000
	s_mov_b32 s12, 0x48000
	s_mov_b32 s13, 0x60000
	s_mov_b32 s14, 0x78000
	s_mov_b32 s15, 0x90000
	s_mov_b32 s16, 0xa8000
	s_mov_b32 s17, 0xc0000
	s_mov_b32 s20, 0xd8000
	s_mov_b32 s21, 0xf0000
	s_mov_b32 s22, 0x108000
	s_mov_b32 s23, 0x120000
	s_mov_b32 s24, 0x138000
	s_mov_b32 s25, 0x150000
	s_mov_b32 s28, 0x168000
	s_mov_b32 s29, s2
	s_mov_b32 s98, 0
	s_branch .LBB8_12

.LBB8_12:
	s_mul_hi_i32 s0, s29, 0x2aaaaaab
	s_lshr_b32 s1, s0, 31
	s_ashr_i32 s0, s0, 4
	s_add_i32 s0, s0, s1
	s_lshl_b32 s1, s0, 9
	v_or_b32_e32 v2, s1, v0
	v_ashrrev_i32_e32 v3, 31, v2
	v_lshl_add_u64 v[2:3], v[2:3], 2, s[54:55]
	v_add_co_u32_e32 v4, vcc, 0x4000, v2
	s_mulk_i32 s0, 0x60
	s_nop 0
	v_addc_co_u32_e32 v5, vcc, 0, v3, vcc
	v_add_co_u32_e32 v6, vcc, s8, v2
	s_sub_i32 s0, s29, s0
	s_nop 0
	v_addc_co_u32_e32 v7, vcc, 0, v3, vcc
	s_cmp_eq_u32 s98, 1
	s_cbranch_scc1 .Lq_p0_w0
	global_load_dword v14, v[2:3], off
.Lq_p0_w0:
	s_cmp_eq_u32 s98, 1
	s_cbranch_scc1 .Lq_p0_w1
	global_load_dword v15, v[4:5], off
.Lq_p0_w1:
	s_cmp_eq_u32 s98, 1
	s_cbranch_scc1 .Lq_p0_w2
	global_load_dword v16, v[6:7], off
.Lq_p0_w2:
	v_add_co_u32_e32 v2, vcc, s9, v2
	s_lshl_b32 s0, s0, 8
	s_nop 0
	v_addc_co_u32_e32 v3, vcc, 0, v3, vcc
	s_cmp_eq_u32 s98, 1
	s_cbranch_scc1 .Lq_p0_w3
	global_load_dword v17, v[2:3], off
.Lq_p0_w3:
	s_cmp_eq_u32 s98, 1
	s_cbranch_scc0 .Lq_p0_cold1
	v_mov_b32_e32 v14, v204
	v_mov_b32_e32 v15, v205
	v_mov_b32_e32 v16, v206
	v_mov_b32_e32 v17, v207
.Lq_p0_cold1:
	s_add_i32 s99, s29, s3
	s_cmpk_gt_i32 s99, 0x2ff
	s_cbranch_scc1 .Lq_p0_nonext
	s_mul_hi_i32 s100, s99, 0x2aaaaaab
	s_lshr_b32 s101, s100, 31
	s_ashr_i32 s100, s100, 4
	s_add_i32 s100, s100, s101
	s_lshl_b32 s101, s100, 9
	v_or_b32_e32 v208, s101, v0
	v_mov_b32_e32 v209, 0
	v_lshl_add_u64 v[208:209], v[208:209], 2, s[54:55]
	global_load_dword v204, v[208:209], off
	v_add_co_u32_e32 v210, vcc, 0x4000, v208
	s_nop 1
	v_addc_co_u32_e32 v211, vcc, 0, v209, vcc
	global_load_dword v205, v[210:211], off
	v_add_co_u32_e32 v210, vcc, s8, v208
	s_nop 1
	v_addc_co_u32_e32 v211, vcc, 0, v209, vcc
	global_load_dword v206, v[210:211], off
	v_add_co_u32_e32 v210, vcc, s9, v208
	s_nop 1
	v_addc_co_u32_e32 v211, vcc, 0, v209, vcc
	global_load_dword v207, v[210:211], off
	s_mulk_i32 s100, 0x60
	s_sub_i32 s100, s99, s100
	s_lshl_b32 s100, s100, 8
	v_or_b32_e32 v200, s100, v67
	v_mov_b32_e32 v201, 0
	v_or_b32_e32 v202, s101, v68
	v_lshlrev_b64 v[200:201], 2, v[200:201]
	v_mad_i64_i32 v[200:201], s[70:71], v202, s10, v[200:201]
	v_lshl_add_u64 v[200:201], s[56:57], 0, v[200:201]
.Lq_p0_nonext:
	v_or_b32_e32 v18, s0, v67
	v_ashrrev_i32_e32 v19, 31, v18
	v_or_b32_e32 v24, s1, v68
	v_lshlrev_b64 v[18:19], 2, v[18:19]
	v_mad_i64_i32 v[18:19], s[70:71], v24, s10, v[18:19]
	s_mov_b64 s[4:5], 0
	v_mov_b32_e32 v54, v74
	v_mov_b32_e32 v10, v55
	v_mov_b32_e32 v11, v55
	v_mov_b32_e32 v12, v55
	v_mov_b32_e32 v13, v55
	v_mov_b32_e32 v6, v55
	v_mov_b32_e32 v7, v55
	v_mov_b32_e32 v8, v55
	v_mov_b32_e32 v9, v55
	v_mov_b32_e32 v2, v55
	v_mov_b32_e32 v3, v55
	v_mov_b32_e32 v4, v55
	v_mov_b32_e32 v5, v55
	v_mov_b32_e32 v60, v55
	v_mov_b32_e32 v61, v55
	v_mov_b32_e32 v62, v55
	v_lshl_add_u64 v[58:59], s[56:57], 0, v[18:19]
	s_cmp_eq_u32 s98, 1
	s_cbranch_scc1 .Lq_p0_skipw0
	v_lshl_add_u64 v[64:65], v[58:59], 0, s[4:5]
	v_add_co_u32_e32 v106, vcc, s10, v64
	s_nop 1
	v_addc_co_u32_e32 v107, vcc, 0, v65, vcc
	v_add_co_u32_e32 v110, vcc, s11, v64
	s_nop 1
	global_load_dwordx4 v[102:105], v[64:65], off
	s_nop 0
	v_addc_co_u32_e32 v111, vcc, 0, v65, vcc
	v_add_co_u32_e32 v114, vcc, s12, v64
	s_nop 1
	v_addc_co_u32_e32 v115, vcc, 0, v65, vcc
	v_add_co_u32_e32 v118, vcc, s13, v64
	s_nop 1
	v_addc_co_u32_e32 v119, vcc, 0, v65, vcc
	v_add_co_u32_e32 v122, vcc, s14, v64
	s_nop 1
	v_addc_co_u32_e32 v123, vcc, 0, v65, vcc
	v_add_co_u32_e32 v126, vcc, s15, v64
	s_nop 1
	v_addc_co_u32_e32 v127, vcc, 0, v65, vcc
	v_add_co_u32_e32 v130, vcc, s16, v64
	s_nop 1
	v_addc_co_u32_e32 v131, vcc, 0, v65, vcc
	v_add_co_u32_e32 v134, vcc, s17, v64
	s_nop 1
	v_addc_co_u32_e32 v135, vcc, 0, v65, vcc
	v_add_co_u32_e32 v138, vcc, s20, v64
	s_nop 1
	v_addc_co_u32_e32 v139, vcc, 0, v65, vcc
	v_add_co_u32_e32 v142, vcc, s21, v64
	s_nop 1
	v_addc_co_u32_e32 v143, vcc, 0, v65, vcc
	v_add_co_u32_e32 v146, vcc, s22, v64
	s_nop 1
	v_addc_co_u32_e32 v147, vcc, 0, v65, vcc
	v_add_co_u32_e32 v150, vcc, s23, v64
	s_nop 1
	v_addc_co_u32_e32 v151, vcc, 0, v65, vcc
	v_add_co_u32_e32 v154, vcc, s24, v64
	s_nop 1
	v_addc_co_u32_e32 v155, vcc, 0, v65, vcc
	v_add_co_u32_e32 v158, vcc, s25, v64
	s_nop 1
	v_addc_co_u32_e32 v159, vcc, 0, v65, vcc
	v_add_co_u32_e32 v64, vcc, s28, v64
	s_nop 1
	v_addc_co_u32_e32 v65, vcc, 0, v65, vcc
	global_load_dwordx4 v[106:109], v[106:107], off
	s_nop 0
	global_load_dwordx4 v[110:113], v[110:111], off
	s_nop 0
	global_load_dwordx4 v[114:117], v[114:115], off
	s_nop 0
	global_load_dwordx4 v[118:121], v[118:119], off
	s_nop 0
	global_load_dwordx4 v[122:125], v[122:123], off
	s_nop 0
	global_load_dwordx4 v[126:129], v[126:127], off
	s_nop 0
	global_load_dwordx4 v[130:133], v[130:131], off
	s_nop 0
	global_load_dwordx4 v[134:137], v[134:135], off
	s_nop 0
	global_load_dwordx4 v[138:141], v[138:139], off
	s_nop 0
	global_load_dwordx4 v[142:145], v[142:143], off
	s_nop 0
	global_load_dwordx4 v[146:149], v[146:147], off
	s_nop 0
	global_load_dwordx4 v[150:153], v[150:151], off
	s_nop 0
	global_load_dwordx4 v[154:157], v[154:155], off
	s_nop 0
	global_load_dwordx4 v[158:161], v[158:159], off
	s_nop 0
	global_load_dwordx4 v[162:165], v[64:65], off
.Lq_p0_skipw0:
	v_mov_b32_e32 v63, v55
	s_waitcnt vmcnt(19)
	v_mul_f32_e32 v20, 0xbfb8aa3b, v14
	s_waitcnt vmcnt(18)
	v_mul_f32_e32 v21, 0xbfb8aa3b, v15
	s_waitcnt vmcnt(17)
	v_mul_f32_e32 v22, 0xbfb8aa3b, v16
	v_exp_f32_e32 v20, v20
	v_exp_f32_e32 v21, v21
	v_exp_f32_e32 v22, v22
	v_add_f32_e32 v20, 1.0, v20
	s_waitcnt vmcnt(16)
	v_mul_f32_e32 v23, 0xbfb8aa3b, v17
	v_exp_f32_e32 v23, v23
	v_add_f32_e32 v21, 1.0, v21
	v_add_f32_e32 v22, 1.0, v22
	v_rcp_f32_e32 v20, v20
	v_add_f32_e32 v23, 1.0, v23
	v_rcp_f32_e32 v21, v21
	v_rcp_f32_e32 v22, v22
	v_rcp_f32_e32 v23, v23
	v_pk_mul_f32 v[14:15], v[14:15], v[20:21]
	v_pk_mul_f32 v[16:17], v[16:17], v[22:23]
	ds_write_b128 v66, v[14:17] offset:32768
	s_waitcnt lgkmcnt(0)
	s_barrier
.LBB8_13:
.Lq_p0_loop:
	s_add_u32 s4, s4, 0x180000
	s_addc_u32 s5, s5, 0
	s_cmp_eq_u32 s4, 0x600000
	s_cbranch_scc0 .Lq_p0_own
	s_add_i32 s99, s29, s3
	s_cmpk_gt_i32 s99, 0x2ff
	s_cbranch_scc1 .Lq_p0_drain
	v_mov_b32_e32 v196, v200
	v_mov_b32_e32 v197, v201
	s_mov_b32 s98, 1
	s_branch .Lq_p0_body
.Lq_p0_own:
	v_lshl_add_u64 v[196:197], v[58:59], 0, s[4:5]
.Lq_p0_body:
	ds_read_b128 v[26:29], v54
	ds_read_b128 v[22:25], v54 offset:16
	ds_read_b128 v[18:21], v54 offset:32
	ds_read_b128 v[14:17], v54 offset:48
	ds_read_b128 v[30:33], v54 offset:64
	ds_read_b128 v[34:37], v54 offset:80
	ds_read_b128 v[38:41], v54 offset:96
	ds_read_b128 v[42:45], v54 offset:112
	ds_read_b128 v[46:49], v54 offset:128
	ds_read_b128 v[50:53], v54 offset:144
	ds_read_b128 v[78:81], v54 offset:160
	ds_read_b128 v[82:85], v54 offset:176
	ds_read_b128 v[86:89], v54 offset:192
	ds_read_b128 v[90:93], v54 offset:208
	ds_read_b128 v[94:97], v54 offset:224
	ds_read_b128 v[98:101], v54 offset:240
	s_waitcnt lgkmcnt(0)
	v_mov_b32_e32 v166, v25
	v_mov_b32_e32 v168, v21
	v_mov_b32_e32 v170, v17
	v_mov_b32_e32 v172, v33
	v_mov_b32_e32 v174, v37
	v_mov_b32_e32 v176, v41
	v_mov_b32_e32 v178, v45
	v_mov_b32_e32 v180, v49
	v_mov_b32_e32 v182, v53
	v_mov_b32_e32 v184, v81
	v_mov_b32_e32 v186, v85
	v_mov_b32_e32 v188, v89
	v_mov_b32_e32 v190, v93
	v_mov_b32_e32 v64, v29
	v_mov_b32_e32 v192, v97
	v_mov_b32_e32 v194, v101
	v_add_u32_e32 v54, 0x100, v54
	s_waitcnt vmcnt(15)
	v_pk_fma_f32 v[10:11], v[102:103], v[26:27], v[10:11] op_sel_hi:[1,0,1]
	v_pk_fma_f32 v[12:13], v[104:105], v[26:27], v[12:13] op_sel_hi:[1,0,1]
	v_pk_fma_f32 v[6:7], v[102:103], v[26:27], v[6:7] op_sel:[0,1,0]
	v_pk_fma_f32 v[8:9], v[104:105], v[26:27], v[8:9] op_sel:[0,1,0]
	v_pk_fma_f32 v[2:3], v[102:103], v[28:29], v[2:3] op_sel_hi:[1,0,1]
	v_pk_fma_f32 v[4:5], v[104:105], v[28:29], v[4:5] op_sel_hi:[1,0,1]
	v_pk_fma_f32 v[26:27], v[102:103], v[64:65], v[62:63] op_sel_hi:[1,0,1]
	v_pk_fma_f32 v[28:29], v[104:105], v[64:65], v[60:61] op_sel_hi:[1,0,1]
	global_load_dwordx4 v[102:105], v[196:197], off
	v_add_co_u32_e32 v198, vcc, s10, v196
	s_waitcnt vmcnt(15)
	v_pk_fma_f32 v[10:11], v[106:107], v[22:23], v[10:11] op_sel_hi:[1,0,1]
	v_pk_fma_f32 v[12:13], v[108:109], v[22:23], v[12:13] op_sel_hi:[1,0,1]
	v_pk_fma_f32 v[6:7], v[106:107], v[22:23], v[6:7] op_sel:[0,1,0]
	v_pk_fma_f32 v[8:9], v[108:109], v[22:23], v[8:9] op_sel:[0,1,0]
	v_pk_fma_f32 v[2:3], v[106:107], v[24:25], v[2:3] op_sel_hi:[1,0,1]
	v_pk_fma_f32 v[4:5], v[108:109], v[24:25], v[4:5] op_sel_hi:[1,0,1]
	v_pk_fma_f32 v[22:23], v[106:107], v[166:167], v[26:27] op_sel_hi:[1,0,1]
	v_pk_fma_f32 v[24:25], v[108:109], v[166:167], v[28:29] op_sel_hi:[1,0,1]
	v_addc_co_u32_e32 v199, vcc, 0, v197, vcc
	global_load_dwordx4 v[106:109], v[198:199], off
	v_add_co_u32_e32 v198, vcc, s11, v196
	s_waitcnt vmcnt(15)
	v_pk_fma_f32 v[10:11], v[110:111], v[18:19], v[10:11] op_sel_hi:[1,0,1]
	v_pk_fma_f32 v[12:13], v[112:113], v[18:19], v[12:13] op_sel_hi:[1,0,1]
	v_pk_fma_f32 v[6:7], v[110:111], v[18:19], v[6:7] op_sel:[0,1,0]
	v_pk_fma_f32 v[8:9], v[112:113], v[18:19], v[8:9] op_sel:[0,1,0]
	v_pk_fma_f32 v[2:3], v[110:111], v[20:21], v[2:3] op_sel_hi:[1,0,1]
	v_pk_fma_f32 v[4:5], v[112:113], v[20:21], v[4:5] op_sel_hi:[1,0,1]
	v_pk_fma_f32 v[18:19], v[110:111], v[168:169], v[22:23] op_sel_hi:[1,0,1]
	v_pk_fma_f32 v[20:21], v[112:113], v[168:169], v[24:25] op_sel_hi:[1,0,1]
	v_addc_co_u32_e32 v199, vcc, 0, v197, vcc
	global_load_dwordx4 v[110:113], v[198:199], off
	v_add_co_u32_e32 v198, vcc, s12, v196
	s_waitcnt vmcnt(15)
	v_pk_fma_f32 v[10:11], v[114:115], v[14:15], v[10:11] op_sel_hi:[1,0,1]
	v_pk_fma_f32 v[12:13], v[116:117], v[14:15], v[12:13] op_sel_hi:[1,0,1]
	v_pk_fma_f32 v[6:7], v[114:115], v[14:15], v[6:7] op_sel:[0,1,0]
	v_pk_fma_f32 v[8:9], v[116:117], v[14:15], v[8:9] op_sel:[0,1,0]
	v_pk_fma_f32 v[2:3], v[114:115], v[16:17], v[2:3] op_sel_hi:[1,0,1]
	v_pk_fma_f32 v[4:5], v[116:117], v[16:17], v[4:5] op_sel_hi:[1,0,1]
	v_pk_fma_f32 v[14:15], v[114:115], v[170:171], v[18:19] op_sel_hi:[1,0,1]
	v_pk_fma_f32 v[16:17], v[116:117], v[170:171], v[20:21] op_sel_hi:[1,0,1]
	v_addc_co_u32_e32 v199, vcc, 0, v197, vcc
	global_load_dwordx4 v[114:117], v[198:199], off
	v_add_co_u32_e32 v198, vcc, s13, v196
	s_waitcnt vmcnt(15)
	v_pk_fma_f32 v[10:11], v[118:119], v[30:31], v[10:11] op_sel_hi:[1,0,1]
	v_pk_fma_f32 v[12:13], v[120:121], v[30:31], v[12:13] op_sel_hi:[1,0,1]
	v_pk_fma_f32 v[6:7], v[118:119], v[30:31], v[6:7] op_sel:[0,1,0]
	v_pk_fma_f32 v[8:9], v[120:121], v[30:31], v[8:9] op_sel:[0,1,0]
	v_pk_fma_f32 v[2:3], v[118:119], v[32:33], v[2:3] op_sel_hi:[1,0,1]
	v_pk_fma_f32 v[4:5], v[120:121], v[32:33], v[4:5] op_sel_hi:[1,0,1]
	v_pk_fma_f32 v[14:15], v[118:119], v[172:173], v[14:15] op_sel_hi:[1,0,1]
	v_pk_fma_f32 v[16:17], v[120:121], v[172:173], v[16:17] op_sel_hi:[1,0,1]
	v_addc_co_u32_e32 v199, vcc, 0, v197, vcc
	global_load_dwordx4 v[118:121], v[198:199], off
	v_add_co_u32_e32 v198, vcc, s14, v196
	s_waitcnt vmcnt(15)
	v_pk_fma_f32 v[10:11], v[122:123], v[34:35], v[10:11] op_sel_hi:[1,0,1]
	v_pk_fma_f32 v[12:13], v[124:125], v[34:35], v[12:13] op_sel_hi:[1,0,1]
	v_pk_fma_f32 v[6:7], v[122:123], v[34:35], v[6:7] op_sel:[0,1,0]
	v_pk_fma_f32 v[8:9], v[124:125], v[34:35], v[8:9] op_sel:[0,1,0]
	v_pk_fma_f32 v[2:3], v[122:123], v[36:37], v[2:3] op_sel_hi:[1,0,1]
	v_pk_fma_f32 v[4:5], v[124:125], v[36:37], v[4:5] op_sel_hi:[1,0,1]
	v_pk_fma_f32 v[14:15], v[122:123], v[174:175], v[14:15] op_sel_hi:[1,0,1]
	v_pk_fma_f32 v[16:17], v[124:125], v[174:175], v[16:17] op_sel_hi:[1,0,1]
	v_addc_co_u32_e32 v199, vcc, 0, v197, vcc
	global_load_dwordx4 v[122:125], v[198:199], off
	v_add_co_u32_e32 v198, vcc, s15, v196
	s_waitcnt vmcnt(15)
	v_pk_fma_f32 v[10:11], v[126:127], v[38:39], v[10:11] op_sel_hi:[1,0,1]
	v_pk_fma_f32 v[12:13], v[128:129], v[38:39], v[12:13] op_sel_hi:[1,0,1]
	v_pk_fma_f32 v[6:7], v[126:127], v[38:39], v[6:7] op_sel:[0,1,0]
	v_pk_fma_f32 v[8:9], v[128:129], v[38:39], v[8:9] op_sel:[0,1,0]
	v_pk_fma_f32 v[2:3], v[126:127], v[40:41], v[2:3] op_sel_hi:[1,0,1]
	v_pk_fma_f32 v[4:5], v[128:129], v[40:41], v[4:5] op_sel_hi:[1,0,1]
	v_pk_fma_f32 v[14:15], v[126:127], v[176:177], v[14:15] op_sel_hi:[1,0,1]
	v_pk_fma_f32 v[16:17], v[128:129], v[176:177], v[16:17] op_sel_hi:[1,0,1]
	v_addc_co_u32_e32 v199, vcc, 0, v197, vcc
	global_load_dwordx4 v[126:129], v[198:199], off
	v_add_co_u32_e32 v198, vcc, s16, v196
	s_waitcnt vmcnt(15)
	v_pk_fma_f32 v[10:11], v[130:131], v[42:43], v[10:11] op_sel_hi:[1,0,1]
	v_pk_fma_f32 v[12:13], v[132:133], v[42:43], v[12:13] op_sel_hi:[1,0,1]
	v_pk_fma_f32 v[6:7], v[130:131], v[42:43], v[6:7] op_sel:[0,1,0]
	v_pk_fma_f32 v[8:9], v[132:133], v[42:43], v[8:9] op_sel:[0,1,0]
	v_pk_fma_f32 v[2:3], v[130:131], v[44:45], v[2:3] op_sel_hi:[1,0,1]
	v_pk_fma_f32 v[4:5], v[132:133], v[44:45], v[4:5] op_sel_hi:[1,0,1]
	v_pk_fma_f32 v[14:15], v[130:131], v[178:179], v[14:15] op_sel_hi:[1,0,1]
	v_pk_fma_f32 v[16:17], v[132:133], v[178:179], v[16:17] op_sel_hi:[1,0,1]
	v_addc_co_u32_e32 v199, vcc, 0, v197, vcc
	global_load_dwordx4 v[130:133], v[198:199], off
	v_add_co_u32_e32 v198, vcc, s17, v196
	s_waitcnt vmcnt(15)
	v_pk_fma_f32 v[10:11], v[134:135], v[46:47], v[10:11] op_sel_hi:[1,0,1]
	v_pk_fma_f32 v[12:13], v[136:137], v[46:47], v[12:13] op_sel_hi:[1,0,1]
	v_pk_fma_f32 v[6:7], v[134:135], v[46:47], v[6:7] op_sel:[0,1,0]
	v_pk_fma_f32 v[8:9], v[136:137], v[46:47], v[8:9] op_sel:[0,1,0]
	v_pk_fma_f32 v[2:3], v[134:135], v[48:49], v[2:3] op_sel_hi:[1,0,1]
	v_pk_fma_f32 v[4:5], v[136:137], v[48:49], v[4:5] op_sel_hi:[1,0,1]
	v_pk_fma_f32 v[14:15], v[134:135], v[180:181], v[14:15] op_sel_hi:[1,0,1]
	v_pk_fma_f32 v[16:17], v[136:137], v[180:181], v[16:17] op_sel_hi:[1,0,1]
	v_addc_co_u32_e32 v199, vcc, 0, v197, vcc
	global_load_dwordx4 v[134:137], v[198:199], off
	v_add_co_u32_e32 v198, vcc, s20, v196
	s_waitcnt vmcnt(15)
	v_pk_fma_f32 v[10:11], v[138:139], v[50:51], v[10:11] op_sel_hi:[1,0,1]
	v_pk_fma_f32 v[12:13], v[140:141], v[50:51], v[12:13] op_sel_hi:[1,0,1]
	v_pk_fma_f32 v[6:7], v[138:139], v[50:51], v[6:7] op_sel:[0,1,0]
	v_pk_fma_f32 v[8:9], v[140:141], v[50:51], v[8:9] op_sel:[0,1,0]
	v_pk_fma_f32 v[2:3], v[138:139], v[52:53], v[2:3] op_sel_hi:[1,0,1]
	v_pk_fma_f32 v[4:5], v[140:141], v[52:53], v[4:5] op_sel_hi:[1,0,1]
	v_pk_fma_f32 v[14:15], v[138:139], v[182:183], v[14:15] op_sel_hi:[1,0,1]
	v_pk_fma_f32 v[16:17], v[140:141], v[182:183], v[16:17] op_sel_hi:[1,0,1]
	v_addc_co_u32_e32 v199, vcc, 0, v197, vcc
	global_load_dwordx4 v[138:141], v[198:199], off
	v_add_co_u32_e32 v198, vcc, s21, v196
	s_waitcnt vmcnt(15)
	v_pk_fma_f32 v[10:11], v[142:143], v[78:79], v[10:11] op_sel_hi:[1,0,1]
	v_pk_fma_f32 v[12:13], v[144:145], v[78:79], v[12:13] op_sel_hi:[1,0,1]
	v_pk_fma_f32 v[6:7], v[142:143], v[78:79], v[6:7] op_sel:[0,1,0]
	v_pk_fma_f32 v[8:9], v[144:145], v[78:79], v[8:9] op_sel:[0,1,0]
	v_pk_fma_f32 v[2:3], v[142:143], v[80:81], v[2:3] op_sel_hi:[1,0,1]
	v_pk_fma_f32 v[4:5], v[144:145], v[80:81], v[4:5] op_sel_hi:[1,0,1]
	v_pk_fma_f32 v[14:15], v[142:143], v[184:185], v[14:15] op_sel_hi:[1,0,1]
	v_pk_fma_f32 v[16:17], v[144:145], v[184:185], v[16:17] op_sel_hi:[1,0,1]
	v_addc_co_u32_e32 v199, vcc, 0, v197, vcc
	global_load_dwordx4 v[142:145], v[198:199], off
	v_add_co_u32_e32 v198, vcc, s22, v196
	s_waitcnt vmcnt(15)
	v_pk_fma_f32 v[10:11], v[146:147], v[82:83], v[10:11] op_sel_hi:[1,0,1]
	v_pk_fma_f32 v[12:13], v[148:149], v[82:83], v[12:13] op_sel_hi:[1,0,1]
	v_pk_fma_f32 v[6:7], v[146:147], v[82:83], v[6:7] op_sel:[0,1,0]
	v_pk_fma_f32 v[8:9], v[148:149], v[82:83], v[8:9] op_sel:[0,1,0]
	v_pk_fma_f32 v[2:3], v[146:147], v[84:85], v[2:3] op_sel_hi:[1,0,1]
	v_pk_fma_f32 v[4:5], v[148:149], v[84:85], v[4:5] op_sel_hi:[1,0,1]
	v_pk_fma_f32 v[14:15], v[146:147], v[186:187], v[14:15] op_sel_hi:[1,0,1]
	v_pk_fma_f32 v[16:17], v[148:149], v[186:187], v[16:17] op_sel_hi:[1,0,1]
	v_addc_co_u32_e32 v199, vcc, 0, v197, vcc
	global_load_dwordx4 v[146:149], v[198:199], off
	v_add_co_u32_e32 v198, vcc, s23, v196
	s_waitcnt vmcnt(15)
	v_pk_fma_f32 v[10:11], v[150:151], v[86:87], v[10:11] op_sel_hi:[1,0,1]
	v_pk_fma_f32 v[12:13], v[152:153], v[86:87], v[12:13] op_sel_hi:[1,0,1]
	v_pk_fma_f32 v[6:7], v[150:151], v[86:87], v[6:7] op_sel:[0,1,0]
	v_pk_fma_f32 v[8:9], v[152:153], v[86:87], v[8:9] op_sel:[0,1,0]
	v_pk_fma_f32 v[2:3], v[150:151], v[88:89], v[2:3] op_sel_hi:[1,0,1]
	v_pk_fma_f32 v[4:5], v[152:153], v[88:89], v[4:5] op_sel_hi:[1,0,1]
	v_pk_fma_f32 v[14:15], v[150:151], v[188:189], v[14:15] op_sel_hi:[1,0,1]
	v_pk_fma_f32 v[16:17], v[152:153], v[188:189], v[16:17] op_sel_hi:[1,0,1]
	v_addc_co_u32_e32 v199, vcc, 0, v197, vcc
	global_load_dwordx4 v[150:153], v[198:199], off
	v_add_co_u32_e32 v198, vcc, s24, v196
	s_waitcnt vmcnt(15)
	v_pk_fma_f32 v[10:11], v[154:155], v[90:91], v[10:11] op_sel_hi:[1,0,1]
	v_pk_fma_f32 v[12:13], v[156:157], v[90:91], v[12:13] op_sel_hi:[1,0,1]
	v_pk_fma_f32 v[6:7], v[154:155], v[90:91], v[6:7] op_sel:[0,1,0]
	v_pk_fma_f32 v[8:9], v[156:157], v[90:91], v[8:9] op_sel:[0,1,0]
	v_pk_fma_f32 v[2:3], v[154:155], v[92:93], v[2:3] op_sel_hi:[1,0,1]
	v_pk_fma_f32 v[4:5], v[156:157], v[92:93], v[4:5] op_sel_hi:[1,0,1]
	v_pk_fma_f32 v[14:15], v[154:155], v[190:191], v[14:15] op_sel_hi:[1,0,1]
	v_pk_fma_f32 v[16:17], v[156:157], v[190:191], v[16:17] op_sel_hi:[1,0,1]
	v_addc_co_u32_e32 v199, vcc, 0, v197, vcc
	global_load_dwordx4 v[154:157], v[198:199], off
	v_add_co_u32_e32 v198, vcc, s25, v196
	s_waitcnt vmcnt(15)
	v_pk_fma_f32 v[10:11], v[158:159], v[94:95], v[10:11] op_sel_hi:[1,0,1]
	v_pk_fma_f32 v[12:13], v[160:161], v[94:95], v[12:13] op_sel_hi:[1,0,1]
	v_pk_fma_f32 v[6:7], v[158:159], v[94:95], v[6:7] op_sel:[0,1,0]
	v_pk_fma_f32 v[8:9], v[160:161], v[94:95], v[8:9] op_sel:[0,1,0]
	v_pk_fma_f32 v[2:3], v[158:159], v[96:97], v[2:3] op_sel_hi:[1,0,1]
	v_pk_fma_f32 v[4:5], v[160:161], v[96:97], v[4:5] op_sel_hi:[1,0,1]
	v_pk_fma_f32 v[14:15], v[158:159], v[192:193], v[14:15] op_sel_hi:[1,0,1]
	v_pk_fma_f32 v[16:17], v[160:161], v[192:193], v[16:17] op_sel_hi:[1,0,1]
	v_addc_co_u32_e32 v199, vcc, 0, v197, vcc
	global_load_dwordx4 v[158:161], v[198:199], off
	v_add_co_u32_e32 v198, vcc, s28, v196
	s_waitcnt vmcnt(15)
	v_pk_fma_f32 v[10:11], v[162:163], v[98:99], v[10:11] op_sel_hi:[1,0,1]
	v_pk_fma_f32 v[12:13], v[164:165], v[98:99], v[12:13] op_sel_hi:[1,0,1]
	v_pk_fma_f32 v[6:7], v[162:163], v[98:99], v[6:7] op_sel:[0,1,0]
	v_pk_fma_f32 v[8:9], v[164:165], v[98:99], v[8:9] op_sel:[0,1,0]
	v_pk_fma_f32 v[2:3], v[162:163], v[100:101], v[2:3] op_sel_hi:[1,0,1]
	v_pk_fma_f32 v[4:5], v[164:165], v[100:101], v[4:5] op_sel_hi:[1,0,1]
	v_pk_fma_f32 v[62:63], v[162:163], v[194:195], v[14:15] op_sel_hi:[1,0,1]
	v_pk_fma_f32 v[60:61], v[164:165], v[194:195], v[16:17] op_sel_hi:[1,0,1]
	v_addc_co_u32_e32 v199, vcc, 0, v197, vcc
	global_load_dwordx4 v[162:165], v[198:199], off
	s_cmp_eq_u32 s4, 0x600000
	s_cbranch_scc0 .Lq_p0_loop
	s_branch .Lq_p0_after
.Lq_p0_drain:
	s_mov_b32 s98, 0
	ds_read_b128 v[26:29], v54
	ds_read_b128 v[22:25], v54 offset:16
	ds_read_b128 v[18:21], v54 offset:32
	ds_read_b128 v[14:17], v54 offset:48
	ds_read_b128 v[30:33], v54 offset:64
	ds_read_b128 v[34:37], v54 offset:80
	ds_read_b128 v[38:41], v54 offset:96
	ds_read_b128 v[42:45], v54 offset:112
	ds_read_b128 v[46:49], v54 offset:128
	ds_read_b128 v[50:53], v54 offset:144
	ds_read_b128 v[78:81], v54 offset:160
	ds_read_b128 v[82:85], v54 offset:176
	ds_read_b128 v[86:89], v54 offset:192
	ds_read_b128 v[90:93], v54 offset:208
	ds_read_b128 v[94:97], v54 offset:224
	ds_read_b128 v[98:101], v54 offset:240
	s_waitcnt lgkmcnt(0)
	v_mov_b32_e32 v166, v25
	v_mov_b32_e32 v168, v21
	v_mov_b32_e32 v170, v17
	v_mov_b32_e32 v172, v33
	v_mov_b32_e32 v174, v37
	v_mov_b32_e32 v176, v41
	v_mov_b32_e32 v178, v45
	v_mov_b32_e32 v180, v49
	v_mov_b32_e32 v182, v53
	v_mov_b32_e32 v184, v81
	v_mov_b32_e32 v186, v85
	v_mov_b32_e32 v188, v89
	v_mov_b32_e32 v190, v93
	v_mov_b32_e32 v64, v29
	v_mov_b32_e32 v192, v97
	v_mov_b32_e32 v194, v101
	v_add_u32_e32 v54, 0x100, v54
	s_waitcnt vmcnt(15)
	v_pk_fma_f32 v[10:11], v[102:103], v[26:27], v[10:11] op_sel_hi:[1,0,1]
	v_pk_fma_f32 v[12:13], v[104:105], v[26:27], v[12:13] op_sel_hi:[1,0,1]
	v_pk_fma_f32 v[6:7], v[102:103], v[26:27], v[6:7] op_sel:[0,1,0]
	v_pk_fma_f32 v[8:9], v[104:105], v[26:27], v[8:9] op_sel:[0,1,0]
	v_pk_fma_f32 v[2:3], v[102:103], v[28:29], v[2:3] op_sel_hi:[1,0,1]
	v_pk_fma_f32 v[4:5], v[104:105], v[28:29], v[4:5] op_sel_hi:[1,0,1]
	v_pk_fma_f32 v[26:27], v[102:103], v[64:65], v[62:63] op_sel_hi:[1,0,1]
	v_pk_fma_f32 v[28:29], v[104:105], v[64:65], v[60:61] op_sel_hi:[1,0,1]
	s_waitcnt vmcnt(14)
	v_pk_fma_f32 v[10:11], v[106:107], v[22:23], v[10:11] op_sel_hi:[1,0,1]
	v_pk_fma_f32 v[12:13], v[108:109], v[22:23], v[12:13] op_sel_hi:[1,0,1]
	v_pk_fma_f32 v[6:7], v[106:107], v[22:23], v[6:7] op_sel:[0,1,0]
	v_pk_fma_f32 v[8:9], v[108:109], v[22:23], v[8:9] op_sel:[0,1,0]
	v_pk_fma_f32 v[2:3], v[106:107], v[24:25], v[2:3] op_sel_hi:[1,0,1]
	v_pk_fma_f32 v[4:5], v[108:109], v[24:25], v[4:5] op_sel_hi:[1,0,1]
	v_pk_fma_f32 v[22:23], v[106:107], v[166:167], v[26:27] op_sel_hi:[1,0,1]
	v_pk_fma_f32 v[24:25], v[108:109], v[166:167], v[28:29] op_sel_hi:[1,0,1]
	s_waitcnt vmcnt(13)
	v_pk_fma_f32 v[10:11], v[110:111], v[18:19], v[10:11] op_sel_hi:[1,0,1]
	v_pk_fma_f32 v[12:13], v[112:113], v[18:19], v[12:13] op_sel_hi:[1,0,1]
	v_pk_fma_f32 v[6:7], v[110:111], v[18:19], v[6:7] op_sel:[0,1,0]
	v_pk_fma_f32 v[8:9], v[112:113], v[18:19], v[8:9] op_sel:[0,1,0]
	v_pk_fma_f32 v[2:3], v[110:111], v[20:21], v[2:3] op_sel_hi:[1,0,1]
	v_pk_fma_f32 v[4:5], v[112:113], v[20:21], v[4:5] op_sel_hi:[1,0,1]
	v_pk_fma_f32 v[18:19], v[110:111], v[168:169], v[22:23] op_sel_hi:[1,0,1]
	v_pk_fma_f32 v[20:21], v[112:113], v[168:169], v[24:25] op_sel_hi:[1,0,1]
	s_waitcnt vmcnt(12)
	v_pk_fma_f32 v[10:11], v[114:115], v[14:15], v[10:11] op_sel_hi:[1,0,1]
	v_pk_fma_f32 v[12:13], v[116:117], v[14:15], v[12:13] op_sel_hi:[1,0,1]
	v_pk_fma_f32 v[6:7], v[114:115], v[14:15], v[6:7] op_sel:[0,1,0]
	v_pk_fma_f32 v[8:9], v[116:117], v[14:15], v[8:9] op_sel:[0,1,0]
	v_pk_fma_f32 v[2:3], v[114:115], v[16:17], v[2:3] op_sel_hi:[1,0,1]
	v_pk_fma_f32 v[4:5], v[116:117], v[16:17], v[4:5] op_sel_hi:[1,0,1]
	v_pk_fma_f32 v[14:15], v[114:115], v[170:171], v[18:19] op_sel_hi:[1,0,1]
	v_pk_fma_f32 v[16:17], v[116:117], v[170:171], v[20:21] op_sel_hi:[1,0,1]
	s_waitcnt vmcnt(11)
	v_pk_fma_f32 v[10:11], v[118:119], v[30:31], v[10:11] op_sel_hi:[1,0,1]
	v_pk_fma_f32 v[12:13], v[120:121], v[30:31], v[12:13] op_sel_hi:[1,0,1]
	v_pk_fma_f32 v[6:7], v[118:119], v[30:31], v[6:7] op_sel:[0,1,0]
	v_pk_fma_f32 v[8:9], v[120:121], v[30:31], v[8:9] op_sel:[0,1,0]
	v_pk_fma_f32 v[2:3], v[118:119], v[32:33], v[2:3] op_sel_hi:[1,0,1]
	v_pk_fma_f32 v[4:5], v[120:121], v[32:33], v[4:5] op_sel_hi:[1,0,1]
	v_pk_fma_f32 v[14:15], v[118:119], v[172:173], v[14:15] op_sel_hi:[1,0,1]
	v_pk_fma_f32 v[16:17], v[120:121], v[172:173], v[16:17] op_sel_hi:[1,0,1]
	s_waitcnt vmcnt(10)
	v_pk_fma_f32 v[10:11], v[122:123], v[34:35], v[10:11] op_sel_hi:[1,0,1]
	v_pk_fma_f32 v[12:13], v[124:125], v[34:35], v[12:13] op_sel_hi:[1,0,1]
	v_pk_fma_f32 v[6:7], v[122:123], v[34:35], v[6:7] op_sel:[0,1,0]
	v_pk_fma_f32 v[8:9], v[124:125], v[34:35], v[8:9] op_sel:[0,1,0]
	v_pk_fma_f32 v[2:3], v[122:123], v[36:37], v[2:3] op_sel_hi:[1,0,1]
	v_pk_fma_f32 v[4:5], v[124:125], v[36:37], v[4:5] op_sel_hi:[1,0,1]
	v_pk_fma_f32 v[14:15], v[122:123], v[174:175], v[14:15] op_sel_hi:[1,0,1]
	v_pk_fma_f32 v[16:17], v[124:125], v[174:175], v[16:17] op_sel_hi:[1,0,1]
	s_waitcnt vmcnt(9)
	v_pk_fma_f32 v[10:11], v[126:127], v[38:39], v[10:11] op_sel_hi:[1,0,1]
	v_pk_fma_f32 v[12:13], v[128:129], v[38:39], v[12:13] op_sel_hi:[1,0,1]
	v_pk_fma_f32 v[6:7], v[126:127], v[38:39], v[6:7] op_sel:[0,1,0]
	v_pk_fma_f32 v[8:9], v[128:129], v[38:39], v[8:9] op_sel:[0,1,0]
	v_pk_fma_f32 v[2:3], v[126:127], v[40:41], v[2:3] op_sel_hi:[1,0,1]
	v_pk_fma_f32 v[4:5], v[128:129], v[40:41], v[4:5] op_sel_hi:[1,0,1]
	v_pk_fma_f32 v[14:15], v[126:127], v[176:177], v[14:15] op_sel_hi:[1,0,1]
	v_pk_fma_f32 v[16:17], v[128:129], v[176:177], v[16:17] op_sel_hi:[1,0,1]
	s_waitcnt vmcnt(8)
	v_pk_fma_f32 v[10:11], v[130:131], v[42:43], v[10:11] op_sel_hi:[1,0,1]
	v_pk_fma_f32 v[12:13], v[132:133], v[42:43], v[12:13] op_sel_hi:[1,0,1]
	v_pk_fma_f32 v[6:7], v[130:131], v[42:43], v[6:7] op_sel:[0,1,0]
	v_pk_fma_f32 v[8:9], v[132:133], v[42:43], v[8:9] op_sel:[0,1,0]
	v_pk_fma_f32 v[2:3], v[130:131], v[44:45], v[2:3] op_sel_hi:[1,0,1]
	v_pk_fma_f32 v[4:5], v[132:133], v[44:45], v[4:5] op_sel_hi:[1,0,1]
	v_pk_fma_f32 v[14:15], v[130:131], v[178:179], v[14:15] op_sel_hi:[1,0,1]
	v_pk_fma_f32 v[16:17], v[132:133], v[178:179], v[16:17] op_sel_hi:[1,0,1]
	s_waitcnt vmcnt(7)
	v_pk_fma_f32 v[10:11], v[134:135], v[46:47], v[10:11] op_sel_hi:[1,0,1]
	v_pk_fma_f32 v[12:13], v[136:137], v[46:47], v[12:13] op_sel_hi:[1,0,1]
	v_pk_fma_f32 v[6:7], v[134:135], v[46:47], v[6:7] op_sel:[0,1,0]
	v_pk_fma_f32 v[8:9], v[136:137], v[46:47], v[8:9] op_sel:[0,1,0]
	v_pk_fma_f32 v[2:3], v[134:135], v[48:49], v[2:3] op_sel_hi:[1,0,1]
	v_pk_fma_f32 v[4:5], v[136:137], v[48:49], v[4:5] op_sel_hi:[1,0,1]
	v_pk_fma_f32 v[14:15], v[134:135], v[180:181], v[14:15] op_sel_hi:[1,0,1]
	v_pk_fma_f32 v[16:17], v[136:137], v[180:181], v[16:17] op_sel_hi:[1,0,1]
	s_waitcnt vmcnt(6)
	v_pk_fma_f32 v[10:11], v[138:139], v[50:51], v[10:11] op_sel_hi:[1,0,1]
	v_pk_fma_f32 v[12:13], v[140:141], v[50:51], v[12:13] op_sel_hi:[1,0,1]
	v_pk_fma_f32 v[6:7], v[138:139], v[50:51], v[6:7] op_sel:[0,1,0]
	v_pk_fma_f32 v[8:9], v[140:141], v[50:51], v[8:9] op_sel:[0,1,0]
	v_pk_fma_f32 v[2:3], v[138:139], v[52:53], v[2:3] op_sel_hi:[1,0,1]
	v_pk_fma_f32 v[4:5], v[140:141], v[52:53], v[4:5] op_sel_hi:[1,0,1]
	v_pk_fma_f32 v[14:15], v[138:139], v[182:183], v[14:15] op_sel_hi:[1,0,1]
	v_pk_fma_f32 v[16:17], v[140:141], v[182:183], v[16:17] op_sel_hi:[1,0,1]
	s_waitcnt vmcnt(5)
	v_pk_fma_f32 v[10:11], v[142:143], v[78:79], v[10:11] op_sel_hi:[1,0,1]
	v_pk_fma_f32 v[12:13], v[144:145], v[78:79], v[12:13] op_sel_hi:[1,0,1]
	v_pk_fma_f32 v[6:7], v[142:143], v[78:79], v[6:7] op_sel:[0,1,0]
	v_pk_fma_f32 v[8:9], v[144:145], v[78:79], v[8:9] op_sel:[0,1,0]
	v_pk_fma_f32 v[2:3], v[142:143], v[80:81], v[2:3] op_sel_hi:[1,0,1]
	v_pk_fma_f32 v[4:5], v[144:145], v[80:81], v[4:5] op_sel_hi:[1,0,1]
	v_pk_fma_f32 v[14:15], v[142:143], v[184:185], v[14:15] op_sel_hi:[1,0,1]
	v_pk_fma_f32 v[16:17], v[144:145], v[184:185], v[16:17] op_sel_hi:[1,0,1]
	s_waitcnt vmcnt(4)
	v_pk_fma_f32 v[10:11], v[146:147], v[82:83], v[10:11] op_sel_hi:[1,0,1]
	v_pk_fma_f32 v[12:13], v[148:149], v[82:83], v[12:13] op_sel_hi:[1,0,1]
	v_pk_fma_f32 v[6:7], v[146:147], v[82:83], v[6:7] op_sel:[0,1,0]
	v_pk_fma_f32 v[8:9], v[148:149], v[82:83], v[8:9] op_sel:[0,1,0]
	v_pk_fma_f32 v[2:3], v[146:147], v[84:85], v[2:3] op_sel_hi:[1,0,1]
	v_pk_fma_f32 v[4:5], v[148:149], v[84:85], v[4:5] op_sel_hi:[1,0,1]
	v_pk_fma_f32 v[14:15], v[146:147], v[186:187], v[14:15] op_sel_hi:[1,0,1]
	v_pk_fma_f32 v[16:17], v[148:149], v[186:187], v[16:17] op_sel_hi:[1,0,1]
	s_waitcnt vmcnt(3)
	v_pk_fma_f32 v[10:11], v[150:151], v[86:87], v[10:11] op_sel_hi:[1,0,1]
	v_pk_fma_f32 v[12:13], v[152:153], v[86:87], v[12:13] op_sel_hi:[1,0,1]
	v_pk_fma_f32 v[6:7], v[150:151], v[86:87], v[6:7] op_sel:[0,1,0]
	v_pk_fma_f32 v[8:9], v[152:153], v[86:87], v[8:9] op_sel:[0,1,0]
	v_pk_fma_f32 v[2:3], v[150:151], v[88:89], v[2:3] op_sel_hi:[1,0,1]
	v_pk_fma_f32 v[4:5], v[152:153], v[88:89], v[4:5] op_sel_hi:[1,0,1]
	v_pk_fma_f32 v[14:15], v[150:151], v[188:189], v[14:15] op_sel_hi:[1,0,1]
	v_pk_fma_f32 v[16:17], v[152:153], v[188:189], v[16:17] op_sel_hi:[1,0,1]
	s_waitcnt vmcnt(2)
	v_pk_fma_f32 v[10:11], v[154:155], v[90:91], v[10:11] op_sel_hi:[1,0,1]
	v_pk_fma_f32 v[12:13], v[156:157], v[90:91], v[12:13] op_sel_hi:[1,0,1]
	v_pk_fma_f32 v[6:7], v[154:155], v[90:91], v[6:7] op_sel:[0,1,0]
	v_pk_fma_f32 v[8:9], v[156:157], v[90:91], v[8:9] op_sel:[0,1,0]
	v_pk_fma_f32 v[2:3], v[154:155], v[92:93], v[2:3] op_sel_hi:[1,0,1]
	v_pk_fma_f32 v[4:5], v[156:157], v[92:93], v[4:5] op_sel_hi:[1,0,1]
	v_pk_fma_f32 v[14:15], v[154:155], v[190:191], v[14:15] op_sel_hi:[1,0,1]
	v_pk_fma_f32 v[16:17], v[156:157], v[190:191], v[16:17] op_sel_hi:[1,0,1]
	s_waitcnt vmcnt(1)
	v_pk_fma_f32 v[10:11], v[158:159], v[94:95], v[10:11] op_sel_hi:[1,0,1]
	v_pk_fma_f32 v[12:13], v[160:161], v[94:95], v[12:13] op_sel_hi:[1,0,1]
	v_pk_fma_f32 v[6:7], v[158:159], v[94:95], v[6:7] op_sel:[0,1,0]
	v_pk_fma_f32 v[8:9], v[160:161], v[94:95], v[8:9] op_sel:[0,1,0]
	v_pk_fma_f32 v[2:3], v[158:159], v[96:97], v[2:3] op_sel_hi:[1,0,1]
	v_pk_fma_f32 v[4:5], v[160:161], v[96:97], v[4:5] op_sel_hi:[1,0,1]
	v_pk_fma_f32 v[14:15], v[158:159], v[192:193], v[14:15] op_sel_hi:[1,0,1]
	v_pk_fma_f32 v[16:17], v[160:161], v[192:193], v[16:17] op_sel_hi:[1,0,1]
	s_waitcnt vmcnt(0)
	v_pk_fma_f32 v[10:11], v[162:163], v[98:99], v[10:11] op_sel_hi:[1,0,1]
	v_pk_fma_f32 v[12:13], v[164:165], v[98:99], v[12:13] op_sel_hi:[1,0,1]
	v_pk_fma_f32 v[6:7], v[162:163], v[98:99], v[6:7] op_sel:[0,1,0]
	v_pk_fma_f32 v[8:9], v[164:165], v[98:99], v[8:9] op_sel:[0,1,0]
	v_pk_fma_f32 v[2:3], v[162:163], v[100:101], v[2:3] op_sel_hi:[1,0,1]
	v_pk_fma_f32 v[4:5], v[164:165], v[100:101], v[4:5] op_sel_hi:[1,0,1]
	v_pk_fma_f32 v[62:63], v[162:163], v[194:195], v[14:15] op_sel_hi:[1,0,1]
	v_pk_fma_f32 v[60:61], v[164:165], v[194:195], v[16:17] op_sel_hi:[1,0,1]
.Lq_p0_after:
	s_add_i32 s1, s29, 0x5f
	ds_write_b128 v69, v[10:13]
	ds_write_b128 v69, v[6:9] offset:1024
	ds_write_b128 v69, v[2:5] offset:2048
	ds_write_b32 v70, v62
	ds_write_b32 v71, v63
	ds_write_b32 v72, v60
	ds_write_b32 v73, v61
	s_cmpk_lt_u32 s1, 0xbf
	v_or_b32_sdwa v2, s0, v0 dst_sel:DWORD dst_unused:UNUSED_PAD src0_sel:DWORD src1_sel:BYTE_0
	s_cselect_b64 s[4:5], -1, 0
	s_ashr_i32 s1, s0, 31
	v_ashrrev_i32_e32 v3, 31, v2
	v_lshl_add_u64 v[2:3], v[2:3], 2, s[58:59]
	v_lshl_add_u64 v[4:5], s[0:1], 2, v[56:57]
	s_mov_b64 s[0:1], 0
	v_mov_b32_e32 v6, v77
	v_mov_b32_e32 v7, v76
	v_mov_b32_e32 v8, v75
	s_waitcnt lgkmcnt(0)
	s_barrier
	s_branch .LBB8_16

	.amdhsa_kernel _Z8mega_fwd4Args
		.amdhsa_group_segment_fixed_size 0
		.amdhsa_private_segment_fixed_size 0
		.amdhsa_kernarg_size 472
		.amdhsa_user_sgpr_count 2
		.amdhsa_user_sgpr_dispatch_ptr 0
		.amdhsa_user_sgpr_queue_ptr 0
		.amdhsa_user_sgpr_kernarg_segment_ptr 1
		.amdhsa_user_sgpr_dispatch_id 0
		.amdhsa_user_sgpr_kernarg_preload_length 0
		.amdhsa_user_sgpr_kernarg_preload_offset 0
		.amdhsa_user_sgpr_private_segment_size 0
		.amdhsa_uses_dynamic_stack 0
		.amdhsa_enable_private_segment 0
		.amdhsa_system_sgpr_workgroup_id_x 1
		.amdhsa_system_sgpr_workgroup_id_y 0
		.amdhsa_system_sgpr_workgroup_id_z 0
		.amdhsa_system_sgpr_workgroup_info 0
		.amdhsa_system_vgpr_workitem_id 0
		.amdhsa_next_free_vgpr 256
		.amdhsa_next_free_sgpr 102
		.amdhsa_accum_offset 256
		.amdhsa_reserve_vcc 1
		.amdhsa_float_round_mode_32 0
		.amdhsa_float_round_mode_16_64 0
		.amdhsa_float_denorm_mode_32 3
		.amdhsa_float_denorm_mode_16_64 3
		.amdhsa_dx10_clamp 1
		.amdhsa_ieee_mode 1
		.amdhsa_fp16_overflow 0
		.amdhsa_tg_split 0
		.amdhsa_exception_fp_ieee_invalid_op 0
		.amdhsa_exception_fp_denorm_src 0
		.amdhsa_exception_fp_ieee_div_zero 0
		.amdhsa_exception_fp_ieee_overflow 0
		.amdhsa_exception_fp_ieee_underflow 0
		.amdhsa_exception_fp_ieee_inexact 0
		.amdhsa_exception_int_div_zero 0
	.end_amdhsa_kernel

amdhsa.kernels:
  - .agpr_count:     0
    .args:
      - .address_space:  global
        .offset:         0
        .size:           8
        .value_kind:     global_buffer
      - .address_space:  global
        .offset:         8
        .size:           8
        .value_kind:     global_buffer
      - .address_space:  global
        .offset:         16
        .size:           8
        .value_kind:     global_buffer
      - .address_space:  global
        .offset:         24
        .size:           8
        .value_kind:     global_buffer
      - .address_space:  global
        .offset:         32
        .size:           8
        .value_kind:     global_buffer
      - .address_space:  global
        .offset:         40
        .size:           8
        .value_kind:     global_buffer
    .group_segment_fixed_size: 0
    .kernarg_segment_align: 8
    .kernarg_segment_size: 48
    .language:       OpenCL C
    .language_version:
      - 2
      - 0
    .max_flat_workgroup_size: 256
    .name:           _Z6k_prepPfS_PKfS1_S1_S1_
    .private_segment_fixed_size: 0
    .sgpr_count:     28
    .sgpr_spill_count: 0
    .symbol:         _Z6k_prepPfS_PKfS1_S1_S1_.kd
    .uniform_work_group_size: 1
    .uses_dynamic_stack: false
    .vgpr_count:     42
    .vgpr_spill_count: 0
    .wavefront_size: 64
  - .agpr_count:     0
    .args:
      - .address_space:  global
        .offset:         0
        .size:           8
        .value_kind:     global_buffer
      - .address_space:  global
        .offset:         8
        .size:           8
        .value_kind:     global_buffer
      - .address_space:  global
        .offset:         16
        .size:           8
        .value_kind:     global_buffer
      - .address_space:  global
        .offset:         24
        .size:           8
        .value_kind:     global_buffer
      - .offset:         32
        .size:           4
        .value_kind:     hidden_block_count_x
      - .offset:         36
        .size:           4
        .value_kind:     hidden_block_count_y
      - .offset:         40
        .size:           4
        .value_kind:     hidden_block_count_z
      - .offset:         44
        .size:           2
        .value_kind:     hidden_group_size_x
      - .offset:         46
        .size:           2
        .value_kind:     hidden_group_size_y
      - .offset:         48
        .size:           2
        .value_kind:     hidden_group_size_z
      - .offset:         50
        .size:           2
        .value_kind:     hidden_remainder_x
      - .offset:         52
        .size:           2
        .value_kind:     hidden_remainder_y
      - .offset:         54
        .size:           2
        .value_kind:     hidden_remainder_z
      - .offset:         72
        .size:           8
        .value_kind:     hidden_global_offset_x
      - .offset:         80
        .size:           8
        .value_kind:     hidden_global_offset_y
      - .offset:         88
        .size:           8
        .value_kind:     hidden_global_offset_z
      - .offset:         96
        .size:           2
        .value_kind:     hidden_grid_dims
    .group_segment_fixed_size: 40960
    .kernarg_segment_align: 8
    .kernarg_segment_size: 288
    .language:       OpenCL C
    .language_version:
      - 2
      - 0
    .max_flat_workgroup_size: 512
    .name:           _Z7k_adalnPKfS0_S0_Pf
    .private_segment_fixed_size: 0
    .sgpr_count:     38
    .sgpr_spill_count: 0
    .symbol:         _Z7k_adalnPKfS0_S0_Pf.kd
    .uniform_work_group_size: 1
    .uses_dynamic_stack: false
    .vgpr_count:     100
    .vgpr_spill_count: 0
    .wavefront_size: 64
  - .agpr_count:     0
    .args:
      - .address_space:  global
        .offset:         0
        .size:           8
        .value_kind:     global_buffer
      - .address_space:  global
        .offset:         8
        .size:           8
        .value_kind:     global_buffer
      - .address_space:  global
        .offset:         16
        .size:           8
        .value_kind:     global_buffer
      - .offset:         24
        .size:           4
        .value_kind:     by_value
      - .offset:         28
        .size:           4
        .value_kind:     by_value
      - .address_space:  global
        .offset:         32
        .size:           8
        .value_kind:     global_buffer
      - .offset:         40
        .size:           4
        .value_kind:     hidden_block_count_x
      - .offset:         44
        .size:           4
        .value_kind:     hidden_block_count_y
      - .offset:         48
        .size:           4
        .value_kind:     hidden_block_count_z
      - .offset:         52
        .size:           2
        .value_kind:     hidden_group_size_x
      - .offset:         54
        .size:           2
        .value_kind:     hidden_group_size_y
      - .offset:         56
        .size:           2
        .value_kind:     hidden_group_size_z
      - .offset:         58
        .size:           2
        .value_kind:     hidden_remainder_x
      - .offset:         60
        .size:           2
        .value_kind:     hidden_remainder_y
      - .offset:         62
        .size:           2
        .value_kind:     hidden_remainder_z
      - .offset:         80
        .size:           8
        .value_kind:     hidden_global_offset_x
      - .offset:         88
        .size:           8
        .value_kind:     hidden_global_offset_y
      - .offset:         96
        .size:           8
        .value_kind:     hidden_global_offset_z
      - .offset:         104
        .size:           2
        .value_kind:     hidden_grid_dims
    .group_segment_fixed_size: 0
    .kernarg_segment_align: 8
    .kernarg_segment_size: 296
    .language:       OpenCL C
    .language_version:
      - 2
      - 0
    .max_flat_workgroup_size: 256
    .name:           _Z10k_norm_modPKfS0_S0_iiPt
    .private_segment_fixed_size: 0
    .sgpr_count:     28
    .sgpr_spill_count: 0
    .symbol:         _Z10k_norm_modPKfS0_S0_iiPt.kd
    .uniform_work_group_size: 1
    .uses_dynamic_stack: false
    .vgpr_count:     172
    .vgpr_spill_count: 0
    .wavefront_size: 64
  - .agpr_count:     0
    .args:
      - .address_space:  global
        .offset:         0
        .size:           8
        .value_kind:     global_buffer
      - .address_space:  global
        .offset:         8
        .size:           8
        .value_kind:     global_buffer
      - .address_space:  global
        .offset:         16
        .size:           8
        .value_kind:     global_buffer
      - .address_space:  global
        .offset:         24
        .size:           8
        .value_kind:     global_buffer
      - .address_space:  global
        .offset:         32
        .size:           8
        .value_kind:     global_buffer
      - .address_space:  global
        .offset:         40
        .size:           8
        .value_kind:     global_buffer
      - .offset:         48
        .size:           4
        .value_kind:     hidden_block_count_x
      - .offset:         52
        .size:           4
        .value_kind:     hidden_block_count_y
      - .offset:         56
        .size:           4
        .value_kind:     hidden_block_count_z
      - .offset:         60
        .size:           2
        .value_kind:     hidden_group_size_x
      - .offset:         62
        .size:           2
        .value_kind:     hidden_group_size_y
      - .offset:         64
        .size:           2
        .value_kind:     hidden_group_size_z
      - .offset:         66
        .size:           2
        .value_kind:     hidden_remainder_x
      - .offset:         68
        .size:           2
        .value_kind:     hidden_remainder_y
      - .offset:         70
        .size:           2
        .value_kind:     hidden_remainder_z
      - .offset:         88
        .size:           8
        .value_kind:     hidden_global_offset_x
      - .offset:         96
        .size:           8
        .value_kind:     hidden_global_offset_y
      - .offset:         104
        .size:           8
        .value_kind:     hidden_global_offset_z
      - .offset:         112
        .size:           2
        .value_kind:     hidden_grid_dims
    .group_segment_fixed_size: 0
    .kernarg_segment_align: 8
    .kernarg_segment_size: 304
    .language:       OpenCL C
    .language_version:
      - 2
      - 0
    .max_flat_workgroup_size: 256
    .name:           _Z6k_postPtPKfS1_S1_S1_S1_
    .private_segment_fixed_size: 0
    .sgpr_count:     42
    .sgpr_spill_count: 0
    .symbol:         _Z6k_postPtPKfS1_S1_S1_S1_.kd
    .uniform_work_group_size: 1
    .uses_dynamic_stack: false
    .vgpr_count:     33
    .vgpr_spill_count: 0
    .wavefront_size: 64
  - .agpr_count:     0
    .args:
      - .address_space:  global
        .offset:         0
        .size:           8
        .value_kind:     global_buffer
      - .address_space:  global
        .offset:         8
        .size:           8
        .value_kind:     global_buffer
      - .address_space:  global
        .offset:         16
        .size:           8
        .value_kind:     global_buffer
    .group_segment_fixed_size: 0
    .kernarg_segment_align: 8
    .kernarg_segment_size: 24
    .language:       OpenCL C
    .language_version:
      - 2
      - 0
    .max_flat_workgroup_size: 64
    .name:           _Z8k_cumsumPKfS0_Pf
    .private_segment_fixed_size: 0
    .sgpr_count:     16
    .sgpr_spill_count: 0
    .symbol:         _Z8k_cumsumPKfS0_Pf.kd
    .uniform_work_group_size: 1
    .uses_dynamic_stack: false
    .vgpr_count:     113
    .vgpr_spill_count: 0
    .wavefront_size: 64
  - .agpr_count:     0
    .args:
      - .address_space:  global
        .offset:         0
        .size:           8
        .value_kind:     global_buffer
      - .address_space:  global
        .offset:         8
        .size:           8
        .value_kind:     global_buffer
      - .address_space:  global
        .offset:         16
        .size:           8
        .value_kind:     global_buffer
      - .address_space:  global
        .offset:         24
        .size:           8
        .value_kind:     global_buffer
      - .address_space:  global
        .offset:         32
        .size:           8
        .value_kind:     global_buffer
      - .address_space:  global
        .offset:         40
        .size:           8
        .value_kind:     global_buffer
      - .address_space:  global
        .offset:         48
        .size:           8
        .value_kind:     global_buffer
      - .address_space:  global
        .offset:         56
        .size:           8
        .value_kind:     global_buffer
      - .address_space:  global
        .offset:         64
        .size:           8
        .value_kind:     global_buffer
      - .address_space:  global
        .offset:         72
        .size:           8
        .value_kind:     global_buffer
    .group_segment_fixed_size: 16904
    .kernarg_segment_align: 8
    .kernarg_segment_size: 80
    .language:       OpenCL C
    .language_version:
      - 2
      - 0
    .max_flat_workgroup_size: 128
    .name:           _Z10k_compressPKtPKfS2_S2_S2_S2_S2_S2_PtS3_
    .private_segment_fixed_size: 0
    .sgpr_count:     43
    .sgpr_spill_count: 0
    .symbol:         _Z10k_compressPKtPKfS2_S2_S2_S2_S2_S2_PtS3_.kd
    .uniform_work_group_size: 1
    .uses_dynamic_stack: false
    .vgpr_count:     26
    .vgpr_spill_count: 0
    .wavefront_size: 64
  - .agpr_count:     0
    .args:
      - .address_space:  global
        .offset:         0
        .size:           8
        .value_kind:     global_buffer
      - .address_space:  global
        .offset:         8
        .size:           8
        .value_kind:     global_buffer
      - .address_space:  global
        .offset:         16
        .size:           8
        .value_kind:     global_buffer
      - .address_space:  global
        .offset:         24
        .size:           8
        .value_kind:     global_buffer
      - .address_space:  global
        .offset:         32
        .size:           8
        .value_kind:     global_buffer
    .group_segment_fixed_size: 19136
    .kernarg_segment_align: 8
    .kernarg_segment_size: 40
    .language:       OpenCL C
    .language_version:
      - 2
      - 0
    .max_flat_workgroup_size: 64
    .name:           _Z11k_nsa_naivePKtPKfS0_S0_Pt
    .private_segment_fixed_size: 0
    .sgpr_count:     43
    .sgpr_spill_count: 0
    .symbol:         _Z11k_nsa_naivePKtPKfS0_S0_Pt.kd
    .uniform_work_group_size: 1
    .uses_dynamic_stack: false
    .vgpr_count:     98
    .vgpr_spill_count: 0
    .wavefront_size: 64
  - .agpr_count:     0
    .args:
      - .address_space:  global
        .offset:         0
        .size:           8
        .value_kind:     global_buffer
      - .address_space:  global
        .offset:         8
        .size:           8
        .value_kind:     global_buffer
      - .address_space:  global
        .offset:         16
        .size:           8
        .value_kind:     global_buffer
    .group_segment_fixed_size: 8704
    .kernarg_segment_align: 8
    .kernarg_segment_size: 24
    .language:       OpenCL C
    .language_version:
      - 2
      - 0
    .max_flat_workgroup_size: 64
    .name:           _Z11k_fox_naivePKtPKfPt
    .private_segment_fixed_size: 0
    .sgpr_count:     34
    .sgpr_spill_count: 0
    .symbol:         _Z11k_fox_naivePKtPKfPt.kd
    .uniform_work_group_size: 1
    .uses_dynamic_stack: false
    .vgpr_count:     76
    .vgpr_spill_count: 0
    .wavefront_size: 64
  - .agpr_count:     0
    .args:
      - .offset:         0
        .size:           216
        .value_kind:     by_value
      - .offset:         216
        .size:           4
        .value_kind:     hidden_block_count_x
      - .offset:         220
        .size:           4
        .value_kind:     hidden_block_count_y
      - .offset:         224
        .size:           4
        .value_kind:     hidden_block_count_z
      - .offset:         228
        .size:           2
        .value_kind:     hidden_group_size_x
      - .offset:         230
        .size:           2
        .value_kind:     hidden_group_size_y
      - .offset:         232
        .size:           2
        .value_kind:     hidden_group_size_z
      - .offset:         234
        .size:           2
        .value_kind:     hidden_remainder_x
      - .offset:         236
        .size:           2
        .value_kind:     hidden_remainder_y
      - .offset:         238
        .size:           2
        .value_kind:     hidden_remainder_z
      - .offset:         256
        .size:           8
        .value_kind:     hidden_global_offset_x
      - .offset:         264
        .size:           8
        .value_kind:     hidden_global_offset_y
      - .offset:         272
        .size:           8
        .value_kind:     hidden_global_offset_z
      - .offset:         280
        .size:           2
        .value_kind:     hidden_grid_dims
      - .offset:         336
        .size:           4
        .value_kind:     hidden_dynamic_lds_size
    .group_segment_fixed_size: 0
    .kernarg_segment_align: 8
    .kernarg_segment_size: 472
    .language:       OpenCL C
    .language_version:
      - 2
      - 0
    .max_flat_workgroup_size: 512
    .name:           _Z8mega_fwd4Args
    .private_segment_fixed_size: 0
    .sgpr_count:     108
    .sgpr_spill_count: 87
    .symbol:         _Z8mega_fwd4Args.kd
    .uniform_work_group_size: 1
    .uses_dynamic_stack: false
    .vgpr_count:     256
    .vgpr_spill_count: 0
    .wavefront_size: 64
